# hardening: first k-iteration phases 3/4 use vmcnt(6)/(8) so no epilogue store can be outstanding when their MFMAs overwrite the accumulators those stores read (timing-neutral)
# speedup vs baseline: 1.0082x; 1.0015x over previous
.LBB0_376:
	v_add_u32_e32 v222, 0x18000, v147
	v_add_u32_e32 v223, 0x1c000, v147
	ds_read_b128 v[152:155], v149
	ds_read_b128 v[156:159], v149 offset:1024
	ds_read_b128 v[160:163], v149 offset:2048
	ds_read_b128 v[168:171], v149 offset:3072
	ds_read_b128 v[172:175], v150
	ds_read_b128 v[176:179], v150 offset:1024
	ds_read_b128 v[180:183], v150 offset:2048
	ds_read_b128 v[184:187], v150 offset:3072
	ds_read_b128 v[188:191], v150 offset:4096
	ds_read_b128 v[192:195], v150 offset:5120
	ds_read_b128 v[196:199], v150 offset:6144
	ds_read_b128 v[200:203], v150 offset:7168
	s_ashr_i32 s17, s16, 31
	v_cmp_lt_i64_e32 vcc, s[20:21], v[140:141]
	s_lshl_b64 s[20:21], s[16:17], 20
	s_add_u32 s20, s35, s20
	s_addc_u32 s21, s36, s21
	s_and_b64 s[22:23], vcc, exec
	s_cselect_b32 s17, s21, s25
	s_cselect_b32 s19, s20, s24
	s_ashr_i32 s15, s14, 31
	s_lshl_b64 s[22:23], s[14:15], 20
	s_add_u32 s22, s37, s22
	s_addc_u32 s23, s38, s23
	s_and_b64 s[28:29], vcc, exec
	s_cselect_b32 s15, s23, s27
	s_cselect_b32 s51, s22, s26
	s_add_u32 s24, s24, 0x80080
	s_addc_u32 s25, s25, 0
	s_add_u32 s52, s26, 0x100
	s_addc_u32 s53, s27, 0
	s_mov_b32 s54, -2
	s_add_u32 s26, s24, 0xfff80080
	s_addc_u32 s27, s25, -1
	s_cmp_eq_u32 s54, 28
	s_cselect_b32 s29, s17, s27
	s_cselect_b32 s28, s19, s26
	s_cselect_b32 s27, s15, s53
	s_cselect_b32 s26, s51, s52
	s_add_i32 m0, s39, 0xc000
	s_nop 0
	global_load_lds_dwordx4 v136, s[24:25]
	s_add_i32 m0, s39, 0xe000
	s_nop 0
	global_load_lds_dwordx4 v138, s[24:25]
	s_waitcnt vmcnt(10)
	s_barrier
	s_waitcnt lgkmcnt(0)
	v_mfma_f32_16x16x32_bf16 v[126:129], v[152:155], v[172:175], 0
	ds_read_b128 v[204:207], v151
	v_mfma_f32_16x16x32_bf16 v[122:125], v[160:163], v[172:175], 0
	v_mfma_f32_16x16x32_bf16 v[118:121], v[152:155], v[180:183], 0
	v_mfma_f32_16x16x32_bf16 v[114:117], v[160:163], v[180:183], 0
	v_mfma_f32_16x16x32_bf16 v[102:105], v[152:155], v[188:191], 0
	ds_read_b128 v[208:211], v151 offset:1024
	v_mfma_f32_16x16x32_bf16 v[98:101], v[160:163], v[188:191], 0
	v_mfma_f32_16x16x32_bf16 v[86:89], v[152:155], v[196:199], 0
	v_mfma_f32_16x16x32_bf16 v[82:85], v[160:163], v[196:199], 0
	v_mfma_f32_16x16x32_bf16 v[126:129], v[156:159], v[176:179], v[126:129]
	ds_read_b128 v[212:215], v151 offset:2048
	v_mfma_f32_16x16x32_bf16 v[122:125], v[168:171], v[176:179], v[122:125]
	v_mfma_f32_16x16x32_bf16 v[118:121], v[156:159], v[184:187], v[118:121]
	v_mfma_f32_16x16x32_bf16 v[114:117], v[168:171], v[184:187], v[114:117]
	v_mfma_f32_16x16x32_bf16 v[102:105], v[156:159], v[192:195], v[102:105]
	ds_read_b128 v[216:219], v151 offset:3072
	v_mfma_f32_16x16x32_bf16 v[98:101], v[168:171], v[192:195], v[98:101]
	v_mfma_f32_16x16x32_bf16 v[86:89], v[156:159], v[200:203], v[86:89]
	v_mfma_f32_16x16x32_bf16 v[82:85], v[168:171], v[200:203], v[82:85]
	s_barrier
	s_add_i32 s55, s47, s34
	s_add_u32 s96, s26, 0x80
	s_addc_u32 s97, s27, 0
	s_mov_b32 m0, s55
	s_nop 0
	global_load_lds_dwordx4 v130, s[26:27]
	s_add_i32 m0, s55, 0x2000
	s_nop 0
	global_load_lds_dwordx4 v132, s[26:27]
	s_waitcnt vmcnt(10)
	s_barrier
	s_waitcnt lgkmcnt(0)
	v_mfma_f32_16x16x32_bf16 v[110:113], v[204:207], v[172:175], 0
	ds_read_b128 v[224:227], v150 offset:16384
	v_mfma_f32_16x16x32_bf16 v[106:109], v[212:215], v[172:175], 0
	v_mfma_f32_16x16x32_bf16 v[94:97], v[204:207], v[180:183], 0
	ds_read_b128 v[228:231], v150 offset:17408
	v_mfma_f32_16x16x32_bf16 v[90:93], v[212:215], v[180:183], 0
	v_mfma_f32_16x16x32_bf16 v[78:81], v[204:207], v[188:191], 0
	ds_read_b128 v[232:235], v150 offset:18432
	v_mfma_f32_16x16x32_bf16 v[74:77], v[212:215], v[188:191], 0
	v_mfma_f32_16x16x32_bf16 v[70:73], v[204:207], v[196:199], 0
	ds_read_b128 v[236:239], v150 offset:19456
	v_mfma_f32_16x16x32_bf16 v[66:69], v[212:215], v[196:199], 0
	v_mfma_f32_16x16x32_bf16 v[110:113], v[208:211], v[176:179], v[110:113]
	ds_read_b128 v[240:243], v150 offset:20480
	v_mfma_f32_16x16x32_bf16 v[106:109], v[216:219], v[176:179], v[106:109]
	v_mfma_f32_16x16x32_bf16 v[94:97], v[208:211], v[184:187], v[94:97]
	ds_read_b128 v[244:247], v150 offset:21504
	v_mfma_f32_16x16x32_bf16 v[90:93], v[216:219], v[184:187], v[90:93]
	v_mfma_f32_16x16x32_bf16 v[78:81], v[208:211], v[192:195], v[78:81]
	ds_read_b128 v[248:251], v150 offset:22528
	v_mfma_f32_16x16x32_bf16 v[74:77], v[216:219], v[192:195], v[74:77]
	v_mfma_f32_16x16x32_bf16 v[70:73], v[208:211], v[200:203], v[70:73]
	ds_read_b128 v[164:167], v150 offset:23552
	v_mfma_f32_16x16x32_bf16 v[66:69], v[216:219], v[200:203], v[66:69]
	s_barrier
	s_mov_b32 m0, s39
	s_add_u32 s94, s28, 0x80
	s_addc_u32 s95, s29, 0
	global_load_lds_dwordx4 v130, s[28:29]
	s_mov_b32 m0, s40
	s_nop 0
	global_load_lds_dwordx4 v132, s[28:29]
	s_waitcnt vmcnt(6)
	s_barrier
	s_waitcnt lgkmcnt(0)
	v_mfma_f32_16x16x32_bf16 v[62:65], v[152:155], v[224:227], 0
	ds_read_b128 v[172:175], v150 offset:32768
	v_mfma_f32_16x16x32_bf16 v[58:61], v[160:163], v[224:227], 0
	v_mfma_f32_16x16x32_bf16 v[54:57], v[152:155], v[232:235], 0
	ds_read_b128 v[176:179], v150 offset:33792
	v_mfma_f32_16x16x32_bf16 v[50:53], v[160:163], v[232:235], 0
	v_mfma_f32_16x16x32_bf16 v[38:41], v[152:155], v[240:243], 0
	ds_read_b128 v[180:183], v150 offset:34816
	v_mfma_f32_16x16x32_bf16 v[34:37], v[160:163], v[240:243], 0
	v_mfma_f32_16x16x32_bf16 v[22:25], v[152:155], v[248:251], 0
	ds_read_b128 v[184:187], v150 offset:35840
	v_mfma_f32_16x16x32_bf16 v[18:21], v[160:163], v[248:251], 0
	v_mfma_f32_16x16x32_bf16 v[62:65], v[156:159], v[228:231], v[62:65]
	ds_read_b128 v[188:191], v150 offset:36864
	v_mfma_f32_16x16x32_bf16 v[58:61], v[168:171], v[228:231], v[58:61]
	v_mfma_f32_16x16x32_bf16 v[54:57], v[156:159], v[236:239], v[54:57]
	ds_read_b128 v[192:195], v150 offset:37888
	v_mfma_f32_16x16x32_bf16 v[50:53], v[168:171], v[236:239], v[50:53]
	v_mfma_f32_16x16x32_bf16 v[38:41], v[156:159], v[244:247], v[38:41]
	ds_read_b128 v[196:199], v150 offset:38912
	v_mfma_f32_16x16x32_bf16 v[34:37], v[168:171], v[244:247], v[34:37]
	v_mfma_f32_16x16x32_bf16 v[22:25], v[156:159], v[164:167], v[22:25]
	ds_read_b128 v[200:203], v150 offset:39936
	v_mfma_f32_16x16x32_bf16 v[18:21], v[168:171], v[164:167], v[18:21]
	s_barrier
	s_add_u32 s56, s26, 0x80000
	s_addc_u32 s57, s27, 0
	s_add_i32 s55, s48, s34
	s_mov_b32 m0, s55
	s_nop 0
	global_load_lds_dwordx4 v130, s[56:57]
	s_add_i32 m0, s55, 0x2000
	s_nop 0
	global_load_lds_dwordx4 v132, s[56:57]
	s_waitcnt vmcnt(8)
	s_barrier
	s_waitcnt lgkmcnt(0)
	v_mfma_f32_16x16x32_bf16 v[46:49], v[204:207], v[224:227], 0
	ds_read_b128 v[152:155], v222
	v_mfma_f32_16x16x32_bf16 v[42:45], v[212:215], v[224:227], 0
	v_mfma_f32_16x16x32_bf16 v[30:33], v[204:207], v[232:235], 0
	v_mfma_f32_16x16x32_bf16 v[26:29], v[212:215], v[232:235], 0
	v_mfma_f32_16x16x32_bf16 v[14:17], v[204:207], v[240:243], 0
	ds_read_b128 v[156:159], v222 offset:1024
	v_mfma_f32_16x16x32_bf16 v[10:13], v[212:215], v[240:243], 0
	v_mfma_f32_16x16x32_bf16 v[6:9], v[204:207], v[248:251], 0
	v_mfma_f32_16x16x32_bf16 v[2:5], v[212:215], v[248:251], 0
	v_mfma_f32_16x16x32_bf16 v[46:49], v[208:211], v[228:231], v[46:49]
	ds_read_b128 v[160:163], v222 offset:2048
	v_mfma_f32_16x16x32_bf16 v[42:45], v[216:219], v[228:231], v[42:45]
	v_mfma_f32_16x16x32_bf16 v[30:33], v[208:211], v[236:239], v[30:33]
	v_mfma_f32_16x16x32_bf16 v[26:29], v[216:219], v[236:239], v[26:29]
	v_mfma_f32_16x16x32_bf16 v[14:17], v[208:211], v[244:247], v[14:17]
	ds_read_b128 v[168:171], v222 offset:3072
	v_mfma_f32_16x16x32_bf16 v[10:13], v[216:219], v[244:247], v[10:13]
	v_mfma_f32_16x16x32_bf16 v[6:9], v[208:211], v[164:167], v[6:9]
	v_mfma_f32_16x16x32_bf16 v[2:5], v[216:219], v[164:167], v[2:5]
	s_barrier
	s_add_i32 s55, 0, 0x18000
	s_add_u32 s28, s28, 0x80000
	s_addc_u32 s29, s29, 0
	s_mov_b32 m0, s41
	s_nop 0
	global_load_lds_dwordx4 v130, s[28:29]
	s_mov_b32 m0, s42
	s_nop 0
	global_load_lds_dwordx4 v132, s[28:29]
	s_waitcnt vmcnt(10)
	s_barrier
	s_waitcnt lgkmcnt(0)
	v_mfma_f32_16x16x32_bf16 v[126:129], v[152:155], v[172:175], v[126:129]
	ds_read_b128 v[204:207], v223
	v_mfma_f32_16x16x32_bf16 v[122:125], v[160:163], v[172:175], v[122:125]
	v_mfma_f32_16x16x32_bf16 v[118:121], v[152:155], v[180:183], v[118:121]
	v_mfma_f32_16x16x32_bf16 v[114:117], v[160:163], v[180:183], v[114:117]
	v_mfma_f32_16x16x32_bf16 v[102:105], v[152:155], v[188:191], v[102:105]
	ds_read_b128 v[208:211], v223 offset:1024
	v_mfma_f32_16x16x32_bf16 v[98:101], v[160:163], v[188:191], v[98:101]
	v_mfma_f32_16x16x32_bf16 v[86:89], v[152:155], v[196:199], v[86:89]
	v_mfma_f32_16x16x32_bf16 v[82:85], v[160:163], v[196:199], v[82:85]
	v_mfma_f32_16x16x32_bf16 v[126:129], v[156:159], v[176:179], v[126:129]
	ds_read_b128 v[212:215], v223 offset:2048
	v_mfma_f32_16x16x32_bf16 v[122:125], v[168:171], v[176:179], v[122:125]
	v_mfma_f32_16x16x32_bf16 v[118:121], v[156:159], v[184:187], v[118:121]
	v_mfma_f32_16x16x32_bf16 v[114:117], v[168:171], v[184:187], v[114:117]
	v_mfma_f32_16x16x32_bf16 v[102:105], v[156:159], v[192:195], v[102:105]
	ds_read_b128 v[216:219], v223 offset:3072
	v_mfma_f32_16x16x32_bf16 v[98:101], v[168:171], v[192:195], v[98:101]
	v_mfma_f32_16x16x32_bf16 v[86:89], v[156:159], v[200:203], v[86:89]
	v_mfma_f32_16x16x32_bf16 v[82:85], v[168:171], v[200:203], v[82:85]
	s_barrier
	s_add_i32 s84, 0, 0x1c000
	s_add_i32 s85, s55, s34
	s_mov_b32 m0, s85
	s_nop 0
	global_load_lds_dwordx4 v130, s[96:97]
	s_add_i32 m0, s85, 0x2000
	s_nop 0
	global_load_lds_dwordx4 v132, s[96:97]
	s_waitcnt vmcnt(10)
	s_barrier
	s_waitcnt lgkmcnt(0)
	v_mfma_f32_16x16x32_bf16 v[110:113], v[204:207], v[172:175], v[110:113]
	ds_read_b128 v[224:227], v150 offset:49152
	v_mfma_f32_16x16x32_bf16 v[106:109], v[212:215], v[172:175], v[106:109]
	v_mfma_f32_16x16x32_bf16 v[94:97], v[204:207], v[180:183], v[94:97]
	ds_read_b128 v[228:231], v150 offset:50176
	v_mfma_f32_16x16x32_bf16 v[90:93], v[212:215], v[180:183], v[90:93]
	v_mfma_f32_16x16x32_bf16 v[78:81], v[204:207], v[188:191], v[78:81]
	ds_read_b128 v[232:235], v150 offset:51200
	v_mfma_f32_16x16x32_bf16 v[74:77], v[212:215], v[188:191], v[74:77]
	v_mfma_f32_16x16x32_bf16 v[70:73], v[204:207], v[196:199], v[70:73]
	ds_read_b128 v[236:239], v150 offset:52224
	v_mfma_f32_16x16x32_bf16 v[66:69], v[212:215], v[196:199], v[66:69]
	v_mfma_f32_16x16x32_bf16 v[110:113], v[208:211], v[176:179], v[110:113]
	ds_read_b128 v[240:243], v150 offset:53248
	v_mfma_f32_16x16x32_bf16 v[106:109], v[216:219], v[176:179], v[106:109]
	v_mfma_f32_16x16x32_bf16 v[94:97], v[208:211], v[184:187], v[94:97]
	ds_read_b128 v[244:247], v150 offset:54272
	v_mfma_f32_16x16x32_bf16 v[90:93], v[216:219], v[184:187], v[90:93]
	v_mfma_f32_16x16x32_bf16 v[78:81], v[208:211], v[192:195], v[78:81]
	ds_read_b128 v[248:251], v150 offset:55296
	v_mfma_f32_16x16x32_bf16 v[74:77], v[216:219], v[192:195], v[74:77]
	v_mfma_f32_16x16x32_bf16 v[70:73], v[208:211], v[200:203], v[70:73]
	ds_read_b128 v[164:167], v150 offset:56320
	v_mfma_f32_16x16x32_bf16 v[66:69], v[216:219], v[200:203], v[66:69]
	s_barrier
	s_mov_b32 m0, s45
	s_nop 0
	global_load_lds_dwordx4 v130, s[94:95]
	s_mov_b32 m0, s46
	s_nop 0
	global_load_lds_dwordx4 v132, s[94:95]
	s_waitcnt vmcnt(8)
	s_barrier
	s_waitcnt lgkmcnt(0)
	v_mfma_f32_16x16x32_bf16 v[62:65], v[152:155], v[224:227], v[62:65]
	ds_read_b128 v[172:175], v150
	v_mfma_f32_16x16x32_bf16 v[58:61], v[160:163], v[224:227], v[58:61]
	v_mfma_f32_16x16x32_bf16 v[54:57], v[152:155], v[232:235], v[54:57]
	ds_read_b128 v[176:179], v150 offset:1024
	v_mfma_f32_16x16x32_bf16 v[50:53], v[160:163], v[232:235], v[50:53]
	v_mfma_f32_16x16x32_bf16 v[38:41], v[152:155], v[240:243], v[38:41]
	ds_read_b128 v[180:183], v150 offset:2048
	v_mfma_f32_16x16x32_bf16 v[34:37], v[160:163], v[240:243], v[34:37]
	v_mfma_f32_16x16x32_bf16 v[22:25], v[152:155], v[248:251], v[22:25]
	ds_read_b128 v[184:187], v150 offset:3072
	v_mfma_f32_16x16x32_bf16 v[18:21], v[160:163], v[248:251], v[18:21]
	v_mfma_f32_16x16x32_bf16 v[62:65], v[156:159], v[228:231], v[62:65]
	ds_read_b128 v[188:191], v150 offset:4096
	v_mfma_f32_16x16x32_bf16 v[58:61], v[168:171], v[228:231], v[58:61]
	v_mfma_f32_16x16x32_bf16 v[54:57], v[156:159], v[236:239], v[54:57]
	ds_read_b128 v[192:195], v150 offset:5120
	v_mfma_f32_16x16x32_bf16 v[50:53], v[168:171], v[236:239], v[50:53]
	v_mfma_f32_16x16x32_bf16 v[38:41], v[156:159], v[244:247], v[38:41]
	ds_read_b128 v[196:199], v150 offset:6144
	v_mfma_f32_16x16x32_bf16 v[34:37], v[168:171], v[244:247], v[34:37]
	v_mfma_f32_16x16x32_bf16 v[22:25], v[156:159], v[164:167], v[22:25]
	ds_read_b128 v[200:203], v150 offset:7168
	v_mfma_f32_16x16x32_bf16 v[18:21], v[168:171], v[164:167], v[18:21]
	s_barrier
	s_add_u32 s26, s26, 0x80080
	s_addc_u32 s27, s27, 0
	s_add_i32 s84, s84, s34
	s_mov_b32 m0, s84
	s_nop 0
	global_load_lds_dwordx4 v130, s[26:27]
	s_add_i32 m0, s84, 0x2000
	s_nop 0
	global_load_lds_dwordx4 v132, s[26:27]
	s_waitcnt vmcnt(10)
	s_barrier
	s_waitcnt lgkmcnt(0)
	v_mfma_f32_16x16x32_bf16 v[46:49], v[204:207], v[224:227], v[46:49]
	ds_read_b128 v[152:155], v149
	v_mfma_f32_16x16x32_bf16 v[42:45], v[212:215], v[224:227], v[42:45]
	v_mfma_f32_16x16x32_bf16 v[30:33], v[204:207], v[232:235], v[30:33]
	v_mfma_f32_16x16x32_bf16 v[26:29], v[212:215], v[232:235], v[26:29]
	v_mfma_f32_16x16x32_bf16 v[14:17], v[204:207], v[240:243], v[14:17]
	ds_read_b128 v[156:159], v149 offset:1024
	v_mfma_f32_16x16x32_bf16 v[10:13], v[212:215], v[240:243], v[10:13]
	v_mfma_f32_16x16x32_bf16 v[6:9], v[204:207], v[248:251], v[6:9]
	v_mfma_f32_16x16x32_bf16 v[2:5], v[212:215], v[248:251], v[2:5]
	v_mfma_f32_16x16x32_bf16 v[46:49], v[208:211], v[228:231], v[46:49]
	ds_read_b128 v[160:163], v149 offset:2048
	v_mfma_f32_16x16x32_bf16 v[42:45], v[216:219], v[228:231], v[42:45]
	v_mfma_f32_16x16x32_bf16 v[30:33], v[208:211], v[236:239], v[30:33]
	v_mfma_f32_16x16x32_bf16 v[26:29], v[216:219], v[236:239], v[26:29]
	v_mfma_f32_16x16x32_bf16 v[14:17], v[208:211], v[244:247], v[14:17]
	ds_read_b128 v[168:171], v149 offset:3072
	v_mfma_f32_16x16x32_bf16 v[10:13], v[216:219], v[244:247], v[10:13]
	v_mfma_f32_16x16x32_bf16 v[6:9], v[208:211], v[164:167], v[6:9]
	v_mfma_f32_16x16x32_bf16 v[2:5], v[216:219], v[164:167], v[2:5]
	s_add_i32 s54, s54, 2
	s_add_u32 s24, s24, 0x100
	s_addc_u32 s25, s25, 0
	s_add_u32 s52, s52, 0x100
	s_addc_u32 s53, s53, 0
	s_cmp_gt_u32 s54, 29
	s_barrier
	s_cbranch_scc0 .LBB0_377
	s_branch .Lp2_loop_exit

.LBB0_944:
	v_add_u32_e32 v158, 0x18000, v164
	v_add_u32_e32 v159, 0x1c000, v164
	ds_read_b128 v[130:133], v167
	ds_read_b128 v[134:137], v167 offset:1024
	ds_read_b128 v[138:141], v167 offset:2048
	ds_read_b128 v[142:145], v167 offset:3072
	ds_read_b128 v[172:175], v170
	ds_read_b128 v[176:179], v170 offset:1024
	ds_read_b128 v[180:183], v170 offset:2048
	ds_read_b128 v[184:187], v170 offset:3072
	ds_read_b128 v[188:191], v170 offset:4096
	ds_read_b128 v[192:195], v170 offset:5120
	ds_read_b128 v[196:199], v170 offset:6144
	ds_read_b128 v[200:203], v170 offset:7168
	s_ashr_i32 s29, s28, 31
	v_cmp_lt_i64_e32 vcc, s[30:31], v[154:155]
	s_lshl_b64 s[30:31], s[28:29], 20
	s_add_u32 s30, s48, s30
	s_addc_u32 s31, s49, s31
	s_and_b64 s[34:35], vcc, exec
	s_cselect_b32 s29, s31, s39
	s_cselect_b32 s63, s30, s38
	s_ashr_i32 s27, s26, 31
	s_lshl_b64 s[34:35], s[26:27], 20
	s_add_u32 s34, s54, s34
	s_addc_u32 s35, s55, s35
	s_and_b64 s[42:43], vcc, exec
	s_cselect_b32 s27, s35, s41
	s_cselect_b32 s64, s34, s40
	s_add_u32 s38, s38, 0x80080
	s_addc_u32 s39, s39, 0
	s_add_u32 s65, s40, 0x100
	s_addc_u32 s66, s41, 0
	s_mov_b32 s67, -2
	s_add_u32 s40, s38, 0xfff80080
	s_addc_u32 s41, s39, -1
	s_cmp_eq_u32 s67, 28
	s_cselect_b32 s43, s29, s41
	s_cselect_b32 s42, s63, s40
	s_cselect_b32 s41, s27, s66
	s_cselect_b32 s40, s64, s65
	s_add_i32 m0, s37, 0xc000
	s_nop 0
	global_load_lds_dwordx4 v150, s[38:39]
	s_add_i32 m0, s37, 0xe000
	s_nop 0
	global_load_lds_dwordx4 v152, s[38:39]
	s_waitcnt vmcnt(10)
	s_barrier
	s_waitcnt lgkmcnt(0)
	v_mfma_f32_16x16x32_bf16 v[126:129], v[130:133], v[172:175], 0
	ds_read_b128 v[204:207], v171
	v_mfma_f32_16x16x32_bf16 v[122:125], v[138:141], v[172:175], 0
	v_mfma_f32_16x16x32_bf16 v[114:117], v[130:133], v[180:183], 0
	v_mfma_f32_16x16x32_bf16 v[106:109], v[138:141], v[180:183], 0
	v_mfma_f32_16x16x32_bf16 v[98:101], v[130:133], v[188:191], 0
	ds_read_b128 v[208:211], v171 offset:1024
	v_mfma_f32_16x16x32_bf16 v[90:93], v[138:141], v[188:191], 0
	v_mfma_f32_16x16x32_bf16 v[82:85], v[130:133], v[196:199], 0
	v_mfma_f32_16x16x32_bf16 v[74:77], v[138:141], v[196:199], 0
	v_mfma_f32_16x16x32_bf16 v[126:129], v[134:137], v[176:179], v[126:129]
	ds_read_b128 v[212:215], v171 offset:2048
	v_mfma_f32_16x16x32_bf16 v[122:125], v[142:145], v[176:179], v[122:125]
	v_mfma_f32_16x16x32_bf16 v[114:117], v[134:137], v[184:187], v[114:117]
	v_mfma_f32_16x16x32_bf16 v[106:109], v[142:145], v[184:187], v[106:109]
	v_mfma_f32_16x16x32_bf16 v[98:101], v[134:137], v[192:195], v[98:101]
	ds_read_b128 v[216:219], v171 offset:3072
	v_mfma_f32_16x16x32_bf16 v[90:93], v[142:145], v[192:195], v[90:93]
	v_mfma_f32_16x16x32_bf16 v[82:85], v[134:137], v[200:203], v[82:85]
	v_mfma_f32_16x16x32_bf16 v[74:77], v[142:145], v[200:203], v[74:77]
	s_barrier
	s_add_i32 s68, s59, s47
	s_add_u32 s96, s40, 0x80
	s_addc_u32 s97, s41, 0
	s_mov_b32 m0, s68
	s_nop 0
	global_load_lds_dwordx4 v146, s[40:41]
	s_add_i32 m0, s68, 0x2000
	s_nop 0
	global_load_lds_dwordx4 v148, s[40:41]
	s_waitcnt vmcnt(10)
	s_barrier
	s_waitcnt lgkmcnt(0)
	v_mfma_f32_16x16x32_bf16 v[118:121], v[204:207], v[172:175], 0
	ds_read_b128 v[224:227], v170 offset:16384
	v_mfma_f32_16x16x32_bf16 v[110:113], v[212:215], v[172:175], 0
	v_mfma_f32_16x16x32_bf16 v[102:105], v[204:207], v[180:183], 0
	ds_read_b128 v[228:231], v170 offset:17408
	v_mfma_f32_16x16x32_bf16 v[94:97], v[212:215], v[180:183], 0
	v_mfma_f32_16x16x32_bf16 v[86:89], v[204:207], v[188:191], 0
	ds_read_b128 v[232:235], v170 offset:18432
	v_mfma_f32_16x16x32_bf16 v[78:81], v[212:215], v[188:191], 0
	v_mfma_f32_16x16x32_bf16 v[70:73], v[204:207], v[196:199], 0
	ds_read_b128 v[236:239], v170 offset:19456
	v_mfma_f32_16x16x32_bf16 v[66:69], v[212:215], v[196:199], 0
	v_mfma_f32_16x16x32_bf16 v[118:121], v[208:211], v[176:179], v[118:121]
	ds_read_b128 v[240:243], v170 offset:20480
	v_mfma_f32_16x16x32_bf16 v[110:113], v[216:219], v[176:179], v[110:113]
	v_mfma_f32_16x16x32_bf16 v[102:105], v[208:211], v[184:187], v[102:105]
	ds_read_b128 v[244:247], v170 offset:21504
	v_mfma_f32_16x16x32_bf16 v[94:97], v[216:219], v[184:187], v[94:97]
	v_mfma_f32_16x16x32_bf16 v[86:89], v[208:211], v[192:195], v[86:89]
	ds_read_b128 v[248:251], v170 offset:22528
	v_mfma_f32_16x16x32_bf16 v[78:81], v[216:219], v[192:195], v[78:81]
	v_mfma_f32_16x16x32_bf16 v[70:73], v[208:211], v[200:203], v[70:73]
	ds_read_b128 v[220:223], v170 offset:23552
	v_mfma_f32_16x16x32_bf16 v[66:69], v[216:219], v[200:203], v[66:69]
	s_barrier
	s_mov_b32 m0, s37
	s_add_u32 s94, s42, 0x80
	s_addc_u32 s95, s43, 0
	global_load_lds_dwordx4 v146, s[42:43]
	s_mov_b32 m0, s50
	s_nop 0
	global_load_lds_dwordx4 v148, s[42:43]
	s_waitcnt vmcnt(6)
	s_barrier
	s_waitcnt lgkmcnt(0)
	v_mfma_f32_16x16x32_bf16 v[62:65], v[130:133], v[224:227], 0
	ds_read_b128 v[172:175], v170 offset:32768
	v_mfma_f32_16x16x32_bf16 v[58:61], v[138:141], v[224:227], 0
	v_mfma_f32_16x16x32_bf16 v[54:57], v[130:133], v[232:235], 0
	ds_read_b128 v[176:179], v170 offset:33792
	v_mfma_f32_16x16x32_bf16 v[46:49], v[138:141], v[232:235], 0
	v_mfma_f32_16x16x32_bf16 v[38:41], v[130:133], v[240:243], 0
	ds_read_b128 v[180:183], v170 offset:34816
	v_mfma_f32_16x16x32_bf16 v[30:33], v[138:141], v[240:243], 0
	v_mfma_f32_16x16x32_bf16 v[22:25], v[130:133], v[248:251], 0
	ds_read_b128 v[184:187], v170 offset:35840
	v_mfma_f32_16x16x32_bf16 v[14:17], v[138:141], v[248:251], 0
	v_mfma_f32_16x16x32_bf16 v[62:65], v[134:137], v[228:231], v[62:65]
	ds_read_b128 v[188:191], v170 offset:36864
	v_mfma_f32_16x16x32_bf16 v[58:61], v[142:145], v[228:231], v[58:61]
	v_mfma_f32_16x16x32_bf16 v[54:57], v[134:137], v[236:239], v[54:57]
	ds_read_b128 v[192:195], v170 offset:37888
	v_mfma_f32_16x16x32_bf16 v[46:49], v[142:145], v[236:239], v[46:49]
	v_mfma_f32_16x16x32_bf16 v[38:41], v[134:137], v[244:247], v[38:41]
	ds_read_b128 v[196:199], v170 offset:38912
	v_mfma_f32_16x16x32_bf16 v[30:33], v[142:145], v[244:247], v[30:33]
	v_mfma_f32_16x16x32_bf16 v[22:25], v[134:137], v[220:223], v[22:25]
	ds_read_b128 v[200:203], v170 offset:39936
	v_mfma_f32_16x16x32_bf16 v[14:17], v[142:145], v[220:223], v[14:17]
	s_barrier
	s_add_u32 s68, s40, 0x80000
	s_addc_u32 s69, s41, 0
	s_add_i32 s70, s60, s47
	s_mov_b32 m0, s70
	s_nop 0
	global_load_lds_dwordx4 v146, s[68:69]
	s_add_i32 m0, s70, 0x2000
	s_nop 0
	global_load_lds_dwordx4 v148, s[68:69]
	s_waitcnt vmcnt(8)
	s_barrier
	s_waitcnt lgkmcnt(0)
	v_mfma_f32_16x16x32_bf16 v[50:53], v[204:207], v[224:227], 0
	ds_read_b128 v[130:133], v158
	v_mfma_f32_16x16x32_bf16 v[42:45], v[212:215], v[224:227], 0
	v_mfma_f32_16x16x32_bf16 v[34:37], v[204:207], v[232:235], 0
	v_mfma_f32_16x16x32_bf16 v[26:29], v[212:215], v[232:235], 0
	v_mfma_f32_16x16x32_bf16 v[18:21], v[204:207], v[240:243], 0
	ds_read_b128 v[134:137], v158 offset:1024
	v_mfma_f32_16x16x32_bf16 v[10:13], v[212:215], v[240:243], 0
	v_mfma_f32_16x16x32_bf16 v[6:9], v[204:207], v[248:251], 0
	v_mfma_f32_16x16x32_bf16 v[2:5], v[212:215], v[248:251], 0
	v_mfma_f32_16x16x32_bf16 v[50:53], v[208:211], v[228:231], v[50:53]
	ds_read_b128 v[138:141], v158 offset:2048
	v_mfma_f32_16x16x32_bf16 v[42:45], v[216:219], v[228:231], v[42:45]
	v_mfma_f32_16x16x32_bf16 v[34:37], v[208:211], v[236:239], v[34:37]
	v_mfma_f32_16x16x32_bf16 v[26:29], v[216:219], v[236:239], v[26:29]
	v_mfma_f32_16x16x32_bf16 v[18:21], v[208:211], v[244:247], v[18:21]
	ds_read_b128 v[142:145], v158 offset:3072
	v_mfma_f32_16x16x32_bf16 v[10:13], v[216:219], v[244:247], v[10:13]
	v_mfma_f32_16x16x32_bf16 v[6:9], v[208:211], v[220:223], v[6:9]
	v_mfma_f32_16x16x32_bf16 v[2:5], v[216:219], v[220:223], v[2:5]
	s_barrier
	s_add_i32 s70, 0, 0x18000
	s_add_u32 s42, s42, 0x80000
	s_addc_u32 s43, s43, 0
	s_mov_b32 m0, s51
	s_nop 0
	global_load_lds_dwordx4 v146, s[42:43]
	s_mov_b32 m0, s52
	s_nop 0
	global_load_lds_dwordx4 v148, s[42:43]
	s_waitcnt vmcnt(10)
	s_barrier
	s_waitcnt lgkmcnt(0)
	v_mfma_f32_16x16x32_bf16 v[126:129], v[130:133], v[172:175], v[126:129]
	ds_read_b128 v[204:207], v159
	v_mfma_f32_16x16x32_bf16 v[122:125], v[138:141], v[172:175], v[122:125]
	v_mfma_f32_16x16x32_bf16 v[114:117], v[130:133], v[180:183], v[114:117]
	v_mfma_f32_16x16x32_bf16 v[106:109], v[138:141], v[180:183], v[106:109]
	v_mfma_f32_16x16x32_bf16 v[98:101], v[130:133], v[188:191], v[98:101]
	ds_read_b128 v[208:211], v159 offset:1024
	v_mfma_f32_16x16x32_bf16 v[90:93], v[138:141], v[188:191], v[90:93]
	v_mfma_f32_16x16x32_bf16 v[82:85], v[130:133], v[196:199], v[82:85]
	v_mfma_f32_16x16x32_bf16 v[74:77], v[138:141], v[196:199], v[74:77]
	v_mfma_f32_16x16x32_bf16 v[126:129], v[134:137], v[176:179], v[126:129]
	ds_read_b128 v[212:215], v159 offset:2048
	v_mfma_f32_16x16x32_bf16 v[122:125], v[142:145], v[176:179], v[122:125]
	v_mfma_f32_16x16x32_bf16 v[114:117], v[134:137], v[184:187], v[114:117]
	v_mfma_f32_16x16x32_bf16 v[106:109], v[142:145], v[184:187], v[106:109]
	v_mfma_f32_16x16x32_bf16 v[98:101], v[134:137], v[192:195], v[98:101]
	ds_read_b128 v[216:219], v159 offset:3072
	v_mfma_f32_16x16x32_bf16 v[90:93], v[142:145], v[192:195], v[90:93]
	v_mfma_f32_16x16x32_bf16 v[82:85], v[134:137], v[200:203], v[82:85]
	v_mfma_f32_16x16x32_bf16 v[74:77], v[142:145], v[200:203], v[74:77]
	s_barrier
	s_add_i32 s84, 0, 0x1c000
	s_add_i32 s85, s70, s47
	s_mov_b32 m0, s85
	s_nop 0
	global_load_lds_dwordx4 v146, s[96:97]
	s_add_i32 m0, s85, 0x2000
	s_nop 0
	global_load_lds_dwordx4 v148, s[96:97]
	s_waitcnt vmcnt(10)
	s_barrier
	s_waitcnt lgkmcnt(0)
	v_mfma_f32_16x16x32_bf16 v[118:121], v[204:207], v[172:175], v[118:121]
	ds_read_b128 v[224:227], v170 offset:49152
	v_mfma_f32_16x16x32_bf16 v[110:113], v[212:215], v[172:175], v[110:113]
	v_mfma_f32_16x16x32_bf16 v[102:105], v[204:207], v[180:183], v[102:105]
	ds_read_b128 v[228:231], v170 offset:50176
	v_mfma_f32_16x16x32_bf16 v[94:97], v[212:215], v[180:183], v[94:97]
	v_mfma_f32_16x16x32_bf16 v[86:89], v[204:207], v[188:191], v[86:89]
	ds_read_b128 v[232:235], v170 offset:51200
	v_mfma_f32_16x16x32_bf16 v[78:81], v[212:215], v[188:191], v[78:81]
	v_mfma_f32_16x16x32_bf16 v[70:73], v[204:207], v[196:199], v[70:73]
	ds_read_b128 v[236:239], v170 offset:52224
	v_mfma_f32_16x16x32_bf16 v[66:69], v[212:215], v[196:199], v[66:69]
	v_mfma_f32_16x16x32_bf16 v[118:121], v[208:211], v[176:179], v[118:121]
	ds_read_b128 v[240:243], v170 offset:53248
	v_mfma_f32_16x16x32_bf16 v[110:113], v[216:219], v[176:179], v[110:113]
	v_mfma_f32_16x16x32_bf16 v[102:105], v[208:211], v[184:187], v[102:105]
	ds_read_b128 v[244:247], v170 offset:54272
	v_mfma_f32_16x16x32_bf16 v[94:97], v[216:219], v[184:187], v[94:97]
	v_mfma_f32_16x16x32_bf16 v[86:89], v[208:211], v[192:195], v[86:89]
	ds_read_b128 v[248:251], v170 offset:55296
	v_mfma_f32_16x16x32_bf16 v[78:81], v[216:219], v[192:195], v[78:81]
	v_mfma_f32_16x16x32_bf16 v[70:73], v[208:211], v[200:203], v[70:73]
	ds_read_b128 v[220:223], v170 offset:56320
	v_mfma_f32_16x16x32_bf16 v[66:69], v[216:219], v[200:203], v[66:69]
	s_barrier
	s_mov_b32 m0, s57
	s_nop 0
	global_load_lds_dwordx4 v146, s[94:95]
	s_mov_b32 m0, s58
	s_nop 0
	global_load_lds_dwordx4 v148, s[94:95]
	s_waitcnt vmcnt(8)
	s_barrier
	s_waitcnt lgkmcnt(0)
	v_mfma_f32_16x16x32_bf16 v[62:65], v[130:133], v[224:227], v[62:65]
	ds_read_b128 v[172:175], v170
	v_mfma_f32_16x16x32_bf16 v[58:61], v[138:141], v[224:227], v[58:61]
	v_mfma_f32_16x16x32_bf16 v[54:57], v[130:133], v[232:235], v[54:57]
	ds_read_b128 v[176:179], v170 offset:1024
	v_mfma_f32_16x16x32_bf16 v[46:49], v[138:141], v[232:235], v[46:49]
	v_mfma_f32_16x16x32_bf16 v[38:41], v[130:133], v[240:243], v[38:41]
	ds_read_b128 v[180:183], v170 offset:2048
	v_mfma_f32_16x16x32_bf16 v[30:33], v[138:141], v[240:243], v[30:33]
	v_mfma_f32_16x16x32_bf16 v[22:25], v[130:133], v[248:251], v[22:25]
	ds_read_b128 v[184:187], v170 offset:3072
	v_mfma_f32_16x16x32_bf16 v[14:17], v[138:141], v[248:251], v[14:17]
	v_mfma_f32_16x16x32_bf16 v[62:65], v[134:137], v[228:231], v[62:65]
	ds_read_b128 v[188:191], v170 offset:4096
	v_mfma_f32_16x16x32_bf16 v[58:61], v[142:145], v[228:231], v[58:61]
	v_mfma_f32_16x16x32_bf16 v[54:57], v[134:137], v[236:239], v[54:57]
	ds_read_b128 v[192:195], v170 offset:5120
	v_mfma_f32_16x16x32_bf16 v[46:49], v[142:145], v[236:239], v[46:49]
	v_mfma_f32_16x16x32_bf16 v[38:41], v[134:137], v[244:247], v[38:41]
	ds_read_b128 v[196:199], v170 offset:6144
	v_mfma_f32_16x16x32_bf16 v[30:33], v[142:145], v[244:247], v[30:33]
	v_mfma_f32_16x16x32_bf16 v[22:25], v[134:137], v[220:223], v[22:25]
	ds_read_b128 v[200:203], v170 offset:7168
	v_mfma_f32_16x16x32_bf16 v[14:17], v[142:145], v[220:223], v[14:17]
	s_barrier
	s_add_u32 s40, s40, 0x80080
	s_addc_u32 s41, s41, 0
	s_add_i32 s84, s84, s47
	s_mov_b32 m0, s84
	s_nop 0
	global_load_lds_dwordx4 v146, s[40:41]
	s_add_i32 m0, s84, 0x2000
	s_nop 0
	global_load_lds_dwordx4 v148, s[40:41]
	s_waitcnt vmcnt(10)
	s_barrier
	s_waitcnt lgkmcnt(0)
	v_mfma_f32_16x16x32_bf16 v[50:53], v[204:207], v[224:227], v[50:53]
	ds_read_b128 v[130:133], v167
	v_mfma_f32_16x16x32_bf16 v[42:45], v[212:215], v[224:227], v[42:45]
	v_mfma_f32_16x16x32_bf16 v[34:37], v[204:207], v[232:235], v[34:37]
	v_mfma_f32_16x16x32_bf16 v[26:29], v[212:215], v[232:235], v[26:29]
	v_mfma_f32_16x16x32_bf16 v[18:21], v[204:207], v[240:243], v[18:21]
	ds_read_b128 v[134:137], v167 offset:1024
	v_mfma_f32_16x16x32_bf16 v[10:13], v[212:215], v[240:243], v[10:13]
	v_mfma_f32_16x16x32_bf16 v[6:9], v[204:207], v[248:251], v[6:9]
	v_mfma_f32_16x16x32_bf16 v[2:5], v[212:215], v[248:251], v[2:5]
	v_mfma_f32_16x16x32_bf16 v[50:53], v[208:211], v[228:231], v[50:53]
	ds_read_b128 v[138:141], v167 offset:2048
	v_mfma_f32_16x16x32_bf16 v[42:45], v[216:219], v[228:231], v[42:45]
	v_mfma_f32_16x16x32_bf16 v[34:37], v[208:211], v[236:239], v[34:37]
	v_mfma_f32_16x16x32_bf16 v[26:29], v[216:219], v[236:239], v[26:29]
	v_mfma_f32_16x16x32_bf16 v[18:21], v[208:211], v[244:247], v[18:21]
	ds_read_b128 v[142:145], v167 offset:3072
	v_mfma_f32_16x16x32_bf16 v[10:13], v[216:219], v[244:247], v[10:13]
	v_mfma_f32_16x16x32_bf16 v[6:9], v[208:211], v[220:223], v[6:9]
	v_mfma_f32_16x16x32_bf16 v[2:5], v[216:219], v[220:223], v[2:5]
	s_add_i32 s67, s67, 2
	s_add_u32 s38, s38, 0x100
	s_addc_u32 s39, s39, 0
	s_add_u32 s65, s65, 0x100
	s_addc_u32 s66, s66, 0
	s_cmp_gt_u32 s67, 29
	s_barrier
	s_cbranch_scc0 .LBB0_945
	s_branch .Lp6_loop_exit

.Lp8_nostage:
	s_add_u32 s50, s48, 0xfff80080
	s_addc_u32 s51, s49, -1
	s_cmp_eq_u32 s80, s87
	s_cselect_b32 s53, s41, s51
	s_cselect_b32 s52, s47, s50
	s_cselect_b32 s51, s39, s75
	s_cselect_b32 s50, s73, s74
	s_add_i32 m0, s21, 0xc000
	s_nop 0
	global_load_lds_dwordx4 v166, s[48:49]
	s_add_i32 m0, s21, 0xe000
	s_nop 0
	global_load_lds_dwordx4 v170, s[48:49]
	s_waitcnt vmcnt(10)
	s_barrier
	s_waitcnt lgkmcnt(0)
	v_mfma_f32_16x16x32_bf16 v[126:129], v[130:133], v[146:149], 0
	ds_read_b128 v[192:195], v242
	v_mfma_f32_16x16x32_bf16 v[122:125], v[138:141], v[146:149], 0
	v_mfma_f32_16x16x32_bf16 v[118:121], v[130:133], v[154:157], 0
	v_mfma_f32_16x16x32_bf16 v[114:117], v[138:141], v[154:157], 0
	v_mfma_f32_16x16x32_bf16 v[106:109], v[130:133], v[176:179], 0
	ds_read_b128 v[196:199], v242 offset:1024
	v_mfma_f32_16x16x32_bf16 v[98:101], v[138:141], v[176:179], 0
	v_mfma_f32_16x16x32_bf16 v[90:93], v[130:133], v[184:187], 0
	v_mfma_f32_16x16x32_bf16 v[82:85], v[138:141], v[184:187], 0
	v_mfma_f32_16x16x32_bf16 v[126:129], v[134:137], v[150:153], v[126:129]
	ds_read_b128 v[200:203], v242 offset:2048
	v_mfma_f32_16x16x32_bf16 v[122:125], v[142:145], v[150:153], v[122:125]
	v_mfma_f32_16x16x32_bf16 v[118:121], v[134:137], v[158:161], v[118:121]
	v_mfma_f32_16x16x32_bf16 v[114:117], v[142:145], v[158:161], v[114:117]
	v_mfma_f32_16x16x32_bf16 v[106:109], v[134:137], v[180:183], v[106:109]
	ds_read_b128 v[204:207], v242 offset:3072
	v_mfma_f32_16x16x32_bf16 v[98:101], v[142:145], v[180:183], v[98:101]
	v_mfma_f32_16x16x32_bf16 v[90:93], v[134:137], v[188:191], v[90:93]
	v_mfma_f32_16x16x32_bf16 v[82:85], v[142:145], v[188:191], v[82:85]
	s_barrier
	s_add_i32 s81, s68, s56
	s_add_u32 s96, s50, 0x80
	s_addc_u32 s97, s51, 0
	s_mov_b32 m0, s81
	s_nop 0
	global_load_lds_dwordx4 v162, s[50:51]
	s_add_i32 m0, s81, 0x2000
	s_nop 0
	global_load_lds_dwordx4 v164, s[50:51]
	s_waitcnt vmcnt(10)
	s_barrier
	s_waitcnt lgkmcnt(0)
	v_mfma_f32_16x16x32_bf16 v[110:113], v[192:195], v[146:149], 0
	ds_read_b128 v[208:211], v241 offset:16384
	v_mfma_f32_16x16x32_bf16 v[102:105], v[200:203], v[146:149], 0
	v_mfma_f32_16x16x32_bf16 v[94:97], v[192:195], v[154:157], 0
	ds_read_b128 v[212:215], v241 offset:17408
	v_mfma_f32_16x16x32_bf16 v[86:89], v[200:203], v[154:157], 0
	v_mfma_f32_16x16x32_bf16 v[78:81], v[192:195], v[176:179], 0
	ds_read_b128 v[216:219], v241 offset:18432
	v_mfma_f32_16x16x32_bf16 v[74:77], v[200:203], v[176:179], 0
	v_mfma_f32_16x16x32_bf16 v[70:73], v[192:195], v[184:187], 0
	ds_read_b128 v[220:223], v241 offset:19456
	v_mfma_f32_16x16x32_bf16 v[66:69], v[200:203], v[184:187], 0
	v_mfma_f32_16x16x32_bf16 v[110:113], v[196:199], v[150:153], v[110:113]
	ds_read_b128 v[224:227], v241 offset:20480
	v_mfma_f32_16x16x32_bf16 v[102:105], v[204:207], v[150:153], v[102:105]
	v_mfma_f32_16x16x32_bf16 v[94:97], v[196:199], v[158:161], v[94:97]
	ds_read_b128 v[228:231], v241 offset:21504
	v_mfma_f32_16x16x32_bf16 v[86:89], v[204:207], v[158:161], v[86:89]
	v_mfma_f32_16x16x32_bf16 v[78:81], v[196:199], v[180:183], v[78:81]
	ds_read_b128 v[232:235], v241 offset:22528
	v_mfma_f32_16x16x32_bf16 v[74:77], v[204:207], v[180:183], v[74:77]
	v_mfma_f32_16x16x32_bf16 v[70:73], v[196:199], v[188:191], v[70:73]
	ds_read_b128 v[246:249], v241 offset:23552
	v_mfma_f32_16x16x32_bf16 v[66:69], v[204:207], v[188:191], v[66:69]
	s_barrier
	s_mov_b32 m0, s21
	s_add_u32 s94, s52, 0x80
	s_addc_u32 s95, s53, 0
	global_load_lds_dwordx4 v162, s[52:53]
	s_mov_b32 m0, s59
	s_nop 0
	global_load_lds_dwordx4 v164, s[52:53]
	s_waitcnt vmcnt(6)
	s_barrier
	s_waitcnt lgkmcnt(0)
	v_mfma_f32_16x16x32_bf16 v[62:65], v[130:133], v[208:211], 0
	ds_read_b128 v[146:149], v241 offset:32768
	v_mfma_f32_16x16x32_bf16 v[58:61], v[138:141], v[208:211], 0
	v_mfma_f32_16x16x32_bf16 v[54:57], v[130:133], v[216:219], 0
	ds_read_b128 v[150:153], v241 offset:33792
	v_mfma_f32_16x16x32_bf16 v[50:53], v[138:141], v[216:219], 0
	v_mfma_f32_16x16x32_bf16 v[42:45], v[130:133], v[224:227], 0
	ds_read_b128 v[154:157], v241 offset:34816
	v_mfma_f32_16x16x32_bf16 v[34:37], v[138:141], v[224:227], 0
	v_mfma_f32_16x16x32_bf16 v[26:29], v[130:133], v[232:235], 0
	ds_read_b128 v[158:161], v241 offset:35840
	v_mfma_f32_16x16x32_bf16 v[18:21], v[138:141], v[232:235], 0
	v_mfma_f32_16x16x32_bf16 v[62:65], v[134:137], v[212:215], v[62:65]
	ds_read_b128 v[176:179], v241 offset:36864
	v_mfma_f32_16x16x32_bf16 v[58:61], v[142:145], v[212:215], v[58:61]
	v_mfma_f32_16x16x32_bf16 v[54:57], v[134:137], v[220:223], v[54:57]
	ds_read_b128 v[180:183], v241 offset:37888
	v_mfma_f32_16x16x32_bf16 v[50:53], v[142:145], v[220:223], v[50:53]
	v_mfma_f32_16x16x32_bf16 v[42:45], v[134:137], v[228:231], v[42:45]
	ds_read_b128 v[184:187], v241 offset:38912
	v_mfma_f32_16x16x32_bf16 v[34:37], v[142:145], v[228:231], v[34:37]
	v_mfma_f32_16x16x32_bf16 v[26:29], v[134:137], v[246:249], v[26:29]
	ds_read_b128 v[188:191], v241 offset:39936
	v_mfma_f32_16x16x32_bf16 v[18:21], v[142:145], v[246:249], v[18:21]
	s_barrier
	s_add_u32 s82, s50, 0x80000
	s_addc_u32 s83, s51, 0
	s_add_i32 s81, s69, s56
	s_mov_b32 m0, s81
	s_nop 0
	global_load_lds_dwordx4 v162, s[82:83]
	s_add_i32 m0, s81, 0x2000
	s_nop 0
	global_load_lds_dwordx4 v164, s[82:83]
	s_waitcnt vmcnt(8)
	s_barrier
	s_waitcnt lgkmcnt(0)
	v_mfma_f32_16x16x32_bf16 v[46:49], v[192:195], v[208:211], 0
	ds_read_b128 v[130:133], v168
	v_mfma_f32_16x16x32_bf16 v[38:41], v[200:203], v[208:211], 0
	v_mfma_f32_16x16x32_bf16 v[30:33], v[192:195], v[216:219], 0
	v_mfma_f32_16x16x32_bf16 v[22:25], v[200:203], v[216:219], 0
	v_mfma_f32_16x16x32_bf16 v[14:17], v[192:195], v[224:227], 0
	ds_read_b128 v[134:137], v168 offset:1024
	v_mfma_f32_16x16x32_bf16 v[10:13], v[200:203], v[224:227], 0
	v_mfma_f32_16x16x32_bf16 v[6:9], v[192:195], v[232:235], 0
	v_mfma_f32_16x16x32_bf16 v[2:5], v[200:203], v[232:235], 0
	v_mfma_f32_16x16x32_bf16 v[46:49], v[196:199], v[212:215], v[46:49]
	ds_read_b128 v[138:141], v168 offset:2048
	v_mfma_f32_16x16x32_bf16 v[38:41], v[204:207], v[212:215], v[38:41]
	v_mfma_f32_16x16x32_bf16 v[30:33], v[196:199], v[220:223], v[30:33]
	v_mfma_f32_16x16x32_bf16 v[22:25], v[204:207], v[220:223], v[22:25]
	v_mfma_f32_16x16x32_bf16 v[14:17], v[196:199], v[228:231], v[14:17]
	ds_read_b128 v[142:145], v168 offset:3072
	v_mfma_f32_16x16x32_bf16 v[10:13], v[204:207], v[228:231], v[10:13]
	v_mfma_f32_16x16x32_bf16 v[6:9], v[196:199], v[246:249], v[6:9]
	v_mfma_f32_16x16x32_bf16 v[2:5], v[204:207], v[246:249], v[2:5]
	s_barrier
	s_add_i32 s81, 0, 0x18000
	s_add_u32 s52, s52, 0x80000
	s_addc_u32 s53, s53, 0
	s_mov_b32 m0, s60
	s_nop 0
	global_load_lds_dwordx4 v162, s[52:53]
	s_mov_b32 m0, s61
	s_nop 0
	global_load_lds_dwordx4 v164, s[52:53]
	s_waitcnt vmcnt(10)
	s_barrier
	s_waitcnt lgkmcnt(0)
	v_mfma_f32_16x16x32_bf16 v[126:129], v[130:133], v[146:149], v[126:129]
	ds_read_b128 v[192:195], v169
	v_mfma_f32_16x16x32_bf16 v[122:125], v[138:141], v[146:149], v[122:125]
	v_mfma_f32_16x16x32_bf16 v[118:121], v[130:133], v[154:157], v[118:121]
	v_mfma_f32_16x16x32_bf16 v[114:117], v[138:141], v[154:157], v[114:117]
	v_mfma_f32_16x16x32_bf16 v[106:109], v[130:133], v[176:179], v[106:109]
	ds_read_b128 v[196:199], v169 offset:1024
	v_mfma_f32_16x16x32_bf16 v[98:101], v[138:141], v[176:179], v[98:101]
	v_mfma_f32_16x16x32_bf16 v[90:93], v[130:133], v[184:187], v[90:93]
	v_mfma_f32_16x16x32_bf16 v[82:85], v[138:141], v[184:187], v[82:85]
	v_mfma_f32_16x16x32_bf16 v[126:129], v[134:137], v[150:153], v[126:129]
	ds_read_b128 v[200:203], v169 offset:2048
	v_mfma_f32_16x16x32_bf16 v[122:125], v[142:145], v[150:153], v[122:125]
	v_mfma_f32_16x16x32_bf16 v[118:121], v[134:137], v[158:161], v[118:121]
	v_mfma_f32_16x16x32_bf16 v[114:117], v[142:145], v[158:161], v[114:117]
	v_mfma_f32_16x16x32_bf16 v[106:109], v[134:137], v[180:183], v[106:109]
	ds_read_b128 v[204:207], v169 offset:3072
	v_mfma_f32_16x16x32_bf16 v[98:101], v[142:145], v[180:183], v[98:101]
	v_mfma_f32_16x16x32_bf16 v[90:93], v[134:137], v[188:191], v[90:93]
	v_mfma_f32_16x16x32_bf16 v[82:85], v[142:145], v[188:191], v[82:85]
	s_barrier
	s_add_i32 s52, 0, 0x1c000
	s_add_i32 s53, s81, s56
	s_mov_b32 m0, s53
	s_nop 0
	global_load_lds_dwordx4 v162, s[96:97]
	s_add_i32 m0, s53, 0x2000
	s_nop 0
	global_load_lds_dwordx4 v164, s[96:97]
	s_waitcnt vmcnt(10)
	s_barrier
	s_waitcnt lgkmcnt(0)
	v_mfma_f32_16x16x32_bf16 v[110:113], v[192:195], v[146:149], v[110:113]
	ds_read_b128 v[208:211], v241 offset:49152
	v_mfma_f32_16x16x32_bf16 v[102:105], v[200:203], v[146:149], v[102:105]
	v_mfma_f32_16x16x32_bf16 v[94:97], v[192:195], v[154:157], v[94:97]
	ds_read_b128 v[212:215], v241 offset:50176
	v_mfma_f32_16x16x32_bf16 v[86:89], v[200:203], v[154:157], v[86:89]
	v_mfma_f32_16x16x32_bf16 v[78:81], v[192:195], v[176:179], v[78:81]
	ds_read_b128 v[216:219], v241 offset:51200
	v_mfma_f32_16x16x32_bf16 v[74:77], v[200:203], v[176:179], v[74:77]
	v_mfma_f32_16x16x32_bf16 v[70:73], v[192:195], v[184:187], v[70:73]
	ds_read_b128 v[220:223], v241 offset:52224
	v_mfma_f32_16x16x32_bf16 v[66:69], v[200:203], v[184:187], v[66:69]
	v_mfma_f32_16x16x32_bf16 v[110:113], v[196:199], v[150:153], v[110:113]
	ds_read_b128 v[224:227], v241 offset:53248
	v_mfma_f32_16x16x32_bf16 v[102:105], v[204:207], v[150:153], v[102:105]
	v_mfma_f32_16x16x32_bf16 v[94:97], v[196:199], v[158:161], v[94:97]
	ds_read_b128 v[228:231], v241 offset:54272
	v_mfma_f32_16x16x32_bf16 v[86:89], v[204:207], v[158:161], v[86:89]
	v_mfma_f32_16x16x32_bf16 v[78:81], v[196:199], v[180:183], v[78:81]
	ds_read_b128 v[232:235], v241 offset:55296
	v_mfma_f32_16x16x32_bf16 v[74:77], v[204:207], v[180:183], v[74:77]
	v_mfma_f32_16x16x32_bf16 v[70:73], v[196:199], v[188:191], v[70:73]
	ds_read_b128 v[246:249], v241 offset:56320
	v_mfma_f32_16x16x32_bf16 v[66:69], v[204:207], v[188:191], v[66:69]
	s_barrier
	s_mov_b32 m0, s64
	s_nop 0
	global_load_lds_dwordx4 v162, s[94:95]
	s_mov_b32 m0, s65
	s_nop 0
	global_load_lds_dwordx4 v164, s[94:95]
	s_waitcnt vmcnt(8)
	s_barrier
	s_waitcnt lgkmcnt(0)
	v_mfma_f32_16x16x32_bf16 v[62:65], v[130:133], v[208:211], v[62:65]
	ds_read_b128 v[146:149], v241
	v_mfma_f32_16x16x32_bf16 v[58:61], v[138:141], v[208:211], v[58:61]
	v_mfma_f32_16x16x32_bf16 v[54:57], v[130:133], v[216:219], v[54:57]
	ds_read_b128 v[150:153], v241 offset:1024
	v_mfma_f32_16x16x32_bf16 v[50:53], v[138:141], v[216:219], v[50:53]
	v_mfma_f32_16x16x32_bf16 v[42:45], v[130:133], v[224:227], v[42:45]
	ds_read_b128 v[154:157], v241 offset:2048
	v_mfma_f32_16x16x32_bf16 v[34:37], v[138:141], v[224:227], v[34:37]
	v_mfma_f32_16x16x32_bf16 v[26:29], v[130:133], v[232:235], v[26:29]
	ds_read_b128 v[158:161], v241 offset:3072
	v_mfma_f32_16x16x32_bf16 v[18:21], v[138:141], v[232:235], v[18:21]
	v_mfma_f32_16x16x32_bf16 v[62:65], v[134:137], v[212:215], v[62:65]
	ds_read_b128 v[176:179], v241 offset:4096
	v_mfma_f32_16x16x32_bf16 v[58:61], v[142:145], v[212:215], v[58:61]
	v_mfma_f32_16x16x32_bf16 v[54:57], v[134:137], v[220:223], v[54:57]
	ds_read_b128 v[180:183], v241 offset:5120
	v_mfma_f32_16x16x32_bf16 v[50:53], v[142:145], v[220:223], v[50:53]
	v_mfma_f32_16x16x32_bf16 v[42:45], v[134:137], v[228:231], v[42:45]
	ds_read_b128 v[184:187], v241 offset:6144
	v_mfma_f32_16x16x32_bf16 v[34:37], v[142:145], v[228:231], v[34:37]
	v_mfma_f32_16x16x32_bf16 v[26:29], v[134:137], v[246:249], v[26:29]
	ds_read_b128 v[188:191], v241 offset:7168
	v_mfma_f32_16x16x32_bf16 v[18:21], v[142:145], v[246:249], v[18:21]
	s_barrier
	s_add_u32 s50, s50, 0x80080
	s_addc_u32 s51, s51, 0
	s_add_i32 s52, s52, s56
	s_mov_b32 m0, s52
	s_nop 0
	global_load_lds_dwordx4 v162, s[50:51]
	s_add_i32 m0, s52, 0x2000
	s_nop 0
	global_load_lds_dwordx4 v164, s[50:51]
	s_waitcnt vmcnt(10)
	s_barrier
	s_waitcnt lgkmcnt(0)
	v_mfma_f32_16x16x32_bf16 v[46:49], v[192:195], v[208:211], v[46:49]
	ds_read_b128 v[130:133], v240
	v_mfma_f32_16x16x32_bf16 v[38:41], v[200:203], v[208:211], v[38:41]
	v_mfma_f32_16x16x32_bf16 v[30:33], v[192:195], v[216:219], v[30:33]
	v_mfma_f32_16x16x32_bf16 v[22:25], v[200:203], v[216:219], v[22:25]
	v_mfma_f32_16x16x32_bf16 v[14:17], v[192:195], v[224:227], v[14:17]
	ds_read_b128 v[134:137], v240 offset:1024
	v_mfma_f32_16x16x32_bf16 v[10:13], v[200:203], v[224:227], v[10:13]
	v_mfma_f32_16x16x32_bf16 v[6:9], v[192:195], v[232:235], v[6:9]
	v_mfma_f32_16x16x32_bf16 v[2:5], v[200:203], v[232:235], v[2:5]
	v_mfma_f32_16x16x32_bf16 v[46:49], v[196:199], v[212:215], v[46:49]
	ds_read_b128 v[138:141], v240 offset:2048
	v_mfma_f32_16x16x32_bf16 v[38:41], v[204:207], v[212:215], v[38:41]
	v_mfma_f32_16x16x32_bf16 v[30:33], v[196:199], v[220:223], v[30:33]
	v_mfma_f32_16x16x32_bf16 v[22:25], v[204:207], v[220:223], v[22:25]
	v_mfma_f32_16x16x32_bf16 v[14:17], v[196:199], v[228:231], v[14:17]
	ds_read_b128 v[142:145], v240 offset:3072
	v_mfma_f32_16x16x32_bf16 v[10:13], v[204:207], v[228:231], v[10:13]
	v_mfma_f32_16x16x32_bf16 v[6:9], v[196:199], v[246:249], v[6:9]
	v_mfma_f32_16x16x32_bf16 v[2:5], v[204:207], v[246:249], v[2:5]
	s_add_i32 s80, s80, 2
	s_add_u32 s48, s48, 0x100
	s_addc_u32 s49, s49, 0
	s_add_u32 s74, s74, 0x100
	s_addc_u32 s75, s75, 0
	s_cmp_gt_u32 s80, s87
	s_barrier
	s_cbranch_scc0 .LBB0_1098
	s_branch .Lp8_loop_exit

.LBB0_1296:
	v_add_u32_e32 v154, 0x18000, v173
	v_add_u32_e32 v155, 0x1c000, v173
	ds_read_b128 v[126:129], v175
	ds_read_b128 v[134:137], v175 offset:1024
	ds_read_b128 v[138:141], v175 offset:2048
	ds_read_b128 v[142:145], v175 offset:3072
	ds_read_b128 v[158:161], v176
	ds_read_b128 v[178:181], v176 offset:1024
	ds_read_b128 v[182:185], v176 offset:2048
	ds_read_b128 v[186:189], v176 offset:3072
	ds_read_b128 v[190:193], v176 offset:4096
	ds_read_b128 v[194:197], v176 offset:5120
	ds_read_b128 v[198:201], v176 offset:6144
	ds_read_b128 v[202:205], v176 offset:7168
	s_add_u32 s28, s28, 0x160080
	s_addc_u32 s29, s29, 0
	s_add_u32 s58, s30, 0x100
	s_addc_u32 s59, s31, 0
	s_mov_b32 s60, -2
	s_add_u32 s30, s28, 0xffea0080
	s_addc_u32 s31, s29, -1
	s_cmpk_eq_i32 s60, 0x54
	s_cselect_b32 s35, s7, s31
	s_cselect_b32 s34, s6, s30
	s_cselect_b32 s31, s9, s59
	s_cselect_b32 s30, s8, s58
	s_add_i32 m0, s43, 0xc000
	s_nop 0
	global_load_lds_dwordx4 v150, s[28:29]
	s_add_i32 m0, s43, 0xe000
	s_nop 0
	global_load_lds_dwordx4 v152, s[28:29]
	s_waitcnt vmcnt(10)
	s_barrier
	s_waitcnt lgkmcnt(0)
	v_mfma_f32_16x16x32_bf16 v[130:133], v[126:129], v[158:161], 0
	ds_read_b128 v[206:209], v177
	v_mfma_f32_16x16x32_bf16 v[122:125], v[138:141], v[158:161], 0
	v_mfma_f32_16x16x32_bf16 v[118:121], v[126:129], v[182:185], 0
	v_mfma_f32_16x16x32_bf16 v[114:117], v[138:141], v[182:185], 0
	v_mfma_f32_16x16x32_bf16 v[102:105], v[126:129], v[190:193], 0
	ds_read_b128 v[210:213], v177 offset:1024
	v_mfma_f32_16x16x32_bf16 v[98:101], v[138:141], v[190:193], 0
	v_mfma_f32_16x16x32_bf16 v[86:89], v[126:129], v[198:201], 0
	v_mfma_f32_16x16x32_bf16 v[82:85], v[138:141], v[198:201], 0
	v_mfma_f32_16x16x32_bf16 v[130:133], v[134:137], v[178:181], v[130:133]
	ds_read_b128 v[214:217], v177 offset:2048
	v_mfma_f32_16x16x32_bf16 v[122:125], v[142:145], v[178:181], v[122:125]
	v_mfma_f32_16x16x32_bf16 v[118:121], v[134:137], v[186:189], v[118:121]
	v_mfma_f32_16x16x32_bf16 v[114:117], v[142:145], v[186:189], v[114:117]
	v_mfma_f32_16x16x32_bf16 v[102:105], v[134:137], v[194:197], v[102:105]
	ds_read_b128 v[218:221], v177 offset:3072
	v_mfma_f32_16x16x32_bf16 v[98:101], v[142:145], v[194:197], v[98:101]
	v_mfma_f32_16x16x32_bf16 v[86:89], v[134:137], v[202:205], v[86:89]
	v_mfma_f32_16x16x32_bf16 v[82:85], v[142:145], v[202:205], v[82:85]
	s_barrier
	s_add_i32 s61, s51, s40
	s_add_u32 s96, s30, 0x80
	s_addc_u32 s97, s31, 0
	s_mov_b32 m0, s61
	s_nop 0
	global_load_lds_dwordx4 v146, s[30:31]
	s_add_i32 m0, s61, 0x2000
	s_nop 0
	global_load_lds_dwordx4 v148, s[30:31]
	s_waitcnt vmcnt(10)
	s_barrier
	s_waitcnt lgkmcnt(0)
	v_mfma_f32_16x16x32_bf16 v[110:113], v[206:209], v[158:161], 0
	ds_read_b128 v[226:229], v176 offset:16384
	v_mfma_f32_16x16x32_bf16 v[106:109], v[214:217], v[158:161], 0
	v_mfma_f32_16x16x32_bf16 v[94:97], v[206:209], v[182:185], 0
	ds_read_b128 v[230:233], v176 offset:17408
	v_mfma_f32_16x16x32_bf16 v[90:93], v[214:217], v[182:185], 0
	v_mfma_f32_16x16x32_bf16 v[78:81], v[206:209], v[190:193], 0
	ds_read_b128 v[234:237], v176 offset:18432
	v_mfma_f32_16x16x32_bf16 v[74:77], v[214:217], v[190:193], 0
	v_mfma_f32_16x16x32_bf16 v[70:73], v[206:209], v[198:201], 0
	ds_read_b128 v[238:241], v176 offset:19456
	v_mfma_f32_16x16x32_bf16 v[66:69], v[214:217], v[198:201], 0
	v_mfma_f32_16x16x32_bf16 v[110:113], v[210:213], v[178:181], v[110:113]
	ds_read_b128 v[242:245], v176 offset:20480
	v_mfma_f32_16x16x32_bf16 v[106:109], v[218:221], v[178:181], v[106:109]
	v_mfma_f32_16x16x32_bf16 v[94:97], v[210:213], v[186:189], v[94:97]
	ds_read_b128 v[246:249], v176 offset:21504
	v_mfma_f32_16x16x32_bf16 v[90:93], v[218:221], v[186:189], v[90:93]
	v_mfma_f32_16x16x32_bf16 v[78:81], v[210:213], v[194:197], v[78:81]
	ds_read_b128 v[250:253], v176 offset:22528
	v_mfma_f32_16x16x32_bf16 v[74:77], v[218:221], v[194:197], v[74:77]
	v_mfma_f32_16x16x32_bf16 v[70:73], v[210:213], v[202:205], v[70:73]
	ds_read_b128 v[222:225], v176 offset:23552
	v_mfma_f32_16x16x32_bf16 v[66:69], v[218:221], v[202:205], v[66:69]
	s_barrier
	s_mov_b32 m0, s43
	s_add_u32 s94, s34, 0x80
	s_addc_u32 s95, s35, 0
	global_load_lds_dwordx4 v146, s[34:35]
	s_mov_b32 m0, s44
	s_nop 0
	global_load_lds_dwordx4 v148, s[34:35]
	s_waitcnt vmcnt(6)
	s_barrier
	s_waitcnt lgkmcnt(0)
	v_mfma_f32_16x16x32_bf16 v[62:65], v[126:129], v[226:229], 0
	ds_read_b128 v[158:161], v176 offset:32768
	v_mfma_f32_16x16x32_bf16 v[58:61], v[138:141], v[226:229], 0
	v_mfma_f32_16x16x32_bf16 v[54:57], v[126:129], v[234:237], 0
	ds_read_b128 v[178:181], v176 offset:33792
	v_mfma_f32_16x16x32_bf16 v[46:49], v[138:141], v[234:237], 0
	v_mfma_f32_16x16x32_bf16 v[38:41], v[126:129], v[242:245], 0
	ds_read_b128 v[182:185], v176 offset:34816
	v_mfma_f32_16x16x32_bf16 v[30:33], v[138:141], v[242:245], 0
	v_mfma_f32_16x16x32_bf16 v[22:25], v[126:129], v[250:253], 0
	ds_read_b128 v[186:189], v176 offset:35840
	v_mfma_f32_16x16x32_bf16 v[14:17], v[138:141], v[250:253], 0
	v_mfma_f32_16x16x32_bf16 v[62:65], v[134:137], v[230:233], v[62:65]
	ds_read_b128 v[190:193], v176 offset:36864
	v_mfma_f32_16x16x32_bf16 v[58:61], v[142:145], v[230:233], v[58:61]
	v_mfma_f32_16x16x32_bf16 v[54:57], v[134:137], v[238:241], v[54:57]
	ds_read_b128 v[194:197], v176 offset:37888
	v_mfma_f32_16x16x32_bf16 v[46:49], v[142:145], v[238:241], v[46:49]
	v_mfma_f32_16x16x32_bf16 v[38:41], v[134:137], v[246:249], v[38:41]
	ds_read_b128 v[198:201], v176 offset:38912
	v_mfma_f32_16x16x32_bf16 v[30:33], v[142:145], v[246:249], v[30:33]
	v_mfma_f32_16x16x32_bf16 v[22:25], v[134:137], v[222:225], v[22:25]
	ds_read_b128 v[202:205], v176 offset:39936
	v_mfma_f32_16x16x32_bf16 v[14:17], v[142:145], v[222:225], v[14:17]
	s_barrier
	s_add_u32 s62, s30, 0x160000
	s_addc_u32 s63, s31, 0
	s_add_i32 s61, s52, s40
	s_mov_b32 m0, s61
	s_nop 0
	global_load_lds_dwordx4 v146, s[62:63]
	s_add_i32 m0, s61, 0x2000
	s_nop 0
	global_load_lds_dwordx4 v148, s[62:63]
	s_waitcnt vmcnt(8)
	s_barrier
	s_waitcnt lgkmcnt(0)
	v_mfma_f32_16x16x32_bf16 v[50:53], v[206:209], v[226:229], 0
	ds_read_b128 v[126:129], v154
	v_mfma_f32_16x16x32_bf16 v[42:45], v[214:217], v[226:229], 0
	v_mfma_f32_16x16x32_bf16 v[34:37], v[206:209], v[234:237], 0
	v_mfma_f32_16x16x32_bf16 v[26:29], v[214:217], v[234:237], 0
	v_mfma_f32_16x16x32_bf16 v[18:21], v[206:209], v[242:245], 0
	ds_read_b128 v[134:137], v154 offset:1024
	v_mfma_f32_16x16x32_bf16 v[10:13], v[214:217], v[242:245], 0
	v_mfma_f32_16x16x32_bf16 v[6:9], v[206:209], v[250:253], 0
	v_mfma_f32_16x16x32_bf16 v[2:5], v[214:217], v[250:253], 0
	v_mfma_f32_16x16x32_bf16 v[50:53], v[210:213], v[230:233], v[50:53]
	ds_read_b128 v[138:141], v154 offset:2048
	v_mfma_f32_16x16x32_bf16 v[42:45], v[218:221], v[230:233], v[42:45]
	v_mfma_f32_16x16x32_bf16 v[34:37], v[210:213], v[238:241], v[34:37]
	v_mfma_f32_16x16x32_bf16 v[26:29], v[218:221], v[238:241], v[26:29]
	v_mfma_f32_16x16x32_bf16 v[18:21], v[210:213], v[246:249], v[18:21]
	ds_read_b128 v[142:145], v154 offset:3072
	v_mfma_f32_16x16x32_bf16 v[10:13], v[218:221], v[246:249], v[10:13]
	v_mfma_f32_16x16x32_bf16 v[6:9], v[210:213], v[222:225], v[6:9]
	v_mfma_f32_16x16x32_bf16 v[2:5], v[218:221], v[222:225], v[2:5]
	s_barrier
	s_add_i32 s61, 0, 0x18000
	s_add_u32 s34, s34, 0x160000
	s_addc_u32 s35, s35, 0
	s_mov_b32 m0, s45
	s_nop 0
	global_load_lds_dwordx4 v146, s[34:35]
	s_mov_b32 m0, s46
	s_nop 0
	global_load_lds_dwordx4 v148, s[34:35]
	s_waitcnt vmcnt(10)
	s_barrier
	s_waitcnt lgkmcnt(0)
	v_mfma_f32_16x16x32_bf16 v[130:133], v[126:129], v[158:161], v[130:133]
	ds_read_b128 v[206:209], v155
	v_mfma_f32_16x16x32_bf16 v[122:125], v[138:141], v[158:161], v[122:125]
	v_mfma_f32_16x16x32_bf16 v[118:121], v[126:129], v[182:185], v[118:121]
	v_mfma_f32_16x16x32_bf16 v[114:117], v[138:141], v[182:185], v[114:117]
	v_mfma_f32_16x16x32_bf16 v[102:105], v[126:129], v[190:193], v[102:105]
	ds_read_b128 v[210:213], v155 offset:1024
	v_mfma_f32_16x16x32_bf16 v[98:101], v[138:141], v[190:193], v[98:101]
	v_mfma_f32_16x16x32_bf16 v[86:89], v[126:129], v[198:201], v[86:89]
	v_mfma_f32_16x16x32_bf16 v[82:85], v[138:141], v[198:201], v[82:85]
	v_mfma_f32_16x16x32_bf16 v[130:133], v[134:137], v[178:181], v[130:133]
	ds_read_b128 v[214:217], v155 offset:2048
	v_mfma_f32_16x16x32_bf16 v[122:125], v[142:145], v[178:181], v[122:125]
	v_mfma_f32_16x16x32_bf16 v[118:121], v[134:137], v[186:189], v[118:121]
	v_mfma_f32_16x16x32_bf16 v[114:117], v[142:145], v[186:189], v[114:117]
	v_mfma_f32_16x16x32_bf16 v[102:105], v[134:137], v[194:197], v[102:105]
	ds_read_b128 v[218:221], v155 offset:3072
	v_mfma_f32_16x16x32_bf16 v[98:101], v[142:145], v[194:197], v[98:101]
	v_mfma_f32_16x16x32_bf16 v[86:89], v[134:137], v[202:205], v[86:89]
	v_mfma_f32_16x16x32_bf16 v[82:85], v[142:145], v[202:205], v[82:85]
	s_barrier
	s_add_i32 s84, 0, 0x1c000
	s_add_i32 s85, s61, s40
	s_mov_b32 m0, s85
	s_nop 0
	global_load_lds_dwordx4 v146, s[96:97]
	s_add_i32 m0, s85, 0x2000
	s_nop 0
	global_load_lds_dwordx4 v148, s[96:97]
	s_waitcnt vmcnt(10)
	s_barrier
	s_waitcnt lgkmcnt(0)
	v_mfma_f32_16x16x32_bf16 v[110:113], v[206:209], v[158:161], v[110:113]
	ds_read_b128 v[226:229], v176 offset:49152
	v_mfma_f32_16x16x32_bf16 v[106:109], v[214:217], v[158:161], v[106:109]
	v_mfma_f32_16x16x32_bf16 v[94:97], v[206:209], v[182:185], v[94:97]
	ds_read_b128 v[230:233], v176 offset:50176
	v_mfma_f32_16x16x32_bf16 v[90:93], v[214:217], v[182:185], v[90:93]
	v_mfma_f32_16x16x32_bf16 v[78:81], v[206:209], v[190:193], v[78:81]
	ds_read_b128 v[234:237], v176 offset:51200
	v_mfma_f32_16x16x32_bf16 v[74:77], v[214:217], v[190:193], v[74:77]
	v_mfma_f32_16x16x32_bf16 v[70:73], v[206:209], v[198:201], v[70:73]
	ds_read_b128 v[238:241], v176 offset:52224
	v_mfma_f32_16x16x32_bf16 v[66:69], v[214:217], v[198:201], v[66:69]
	v_mfma_f32_16x16x32_bf16 v[110:113], v[210:213], v[178:181], v[110:113]
	ds_read_b128 v[242:245], v176 offset:53248
	v_mfma_f32_16x16x32_bf16 v[106:109], v[218:221], v[178:181], v[106:109]
	v_mfma_f32_16x16x32_bf16 v[94:97], v[210:213], v[186:189], v[94:97]
	ds_read_b128 v[246:249], v176 offset:54272
	v_mfma_f32_16x16x32_bf16 v[90:93], v[218:221], v[186:189], v[90:93]
	v_mfma_f32_16x16x32_bf16 v[78:81], v[210:213], v[194:197], v[78:81]
	ds_read_b128 v[250:253], v176 offset:55296
	v_mfma_f32_16x16x32_bf16 v[74:77], v[218:221], v[194:197], v[74:77]
	v_mfma_f32_16x16x32_bf16 v[70:73], v[210:213], v[202:205], v[70:73]
	ds_read_b128 v[222:225], v176 offset:56320
	v_mfma_f32_16x16x32_bf16 v[66:69], v[218:221], v[202:205], v[66:69]
	s_barrier
	s_mov_b32 m0, s48
	s_nop 0
	global_load_lds_dwordx4 v146, s[94:95]
	s_mov_b32 m0, s49
	s_nop 0
	global_load_lds_dwordx4 v148, s[94:95]
	s_waitcnt vmcnt(8)
	s_barrier
	s_waitcnt lgkmcnt(0)
	v_mfma_f32_16x16x32_bf16 v[62:65], v[126:129], v[226:229], v[62:65]
	ds_read_b128 v[158:161], v176
	v_mfma_f32_16x16x32_bf16 v[58:61], v[138:141], v[226:229], v[58:61]
	v_mfma_f32_16x16x32_bf16 v[54:57], v[126:129], v[234:237], v[54:57]
	ds_read_b128 v[178:181], v176 offset:1024
	v_mfma_f32_16x16x32_bf16 v[46:49], v[138:141], v[234:237], v[46:49]
	v_mfma_f32_16x16x32_bf16 v[38:41], v[126:129], v[242:245], v[38:41]
	ds_read_b128 v[182:185], v176 offset:2048
	v_mfma_f32_16x16x32_bf16 v[30:33], v[138:141], v[242:245], v[30:33]
	v_mfma_f32_16x16x32_bf16 v[22:25], v[126:129], v[250:253], v[22:25]
	ds_read_b128 v[186:189], v176 offset:3072
	v_mfma_f32_16x16x32_bf16 v[14:17], v[138:141], v[250:253], v[14:17]
	v_mfma_f32_16x16x32_bf16 v[62:65], v[134:137], v[230:233], v[62:65]
	ds_read_b128 v[190:193], v176 offset:4096
	v_mfma_f32_16x16x32_bf16 v[58:61], v[142:145], v[230:233], v[58:61]
	v_mfma_f32_16x16x32_bf16 v[54:57], v[134:137], v[238:241], v[54:57]
	ds_read_b128 v[194:197], v176 offset:5120
	v_mfma_f32_16x16x32_bf16 v[46:49], v[142:145], v[238:241], v[46:49]
	v_mfma_f32_16x16x32_bf16 v[38:41], v[134:137], v[246:249], v[38:41]
	ds_read_b128 v[198:201], v176 offset:6144
	v_mfma_f32_16x16x32_bf16 v[30:33], v[142:145], v[246:249], v[30:33]
	v_mfma_f32_16x16x32_bf16 v[22:25], v[134:137], v[222:225], v[22:25]
	ds_read_b128 v[202:205], v176 offset:7168
	v_mfma_f32_16x16x32_bf16 v[14:17], v[142:145], v[222:225], v[14:17]
	s_barrier
	s_add_u32 s30, s30, 0x160080
	s_addc_u32 s31, s31, 0
	s_add_i32 s84, s84, s40
	s_mov_b32 m0, s84
	s_nop 0
	global_load_lds_dwordx4 v146, s[30:31]
	s_add_i32 m0, s84, 0x2000
	s_nop 0
	global_load_lds_dwordx4 v148, s[30:31]
	s_waitcnt vmcnt(10)
	s_barrier
	s_waitcnt lgkmcnt(0)
	v_mfma_f32_16x16x32_bf16 v[50:53], v[206:209], v[226:229], v[50:53]
	ds_read_b128 v[126:129], v175
	v_mfma_f32_16x16x32_bf16 v[42:45], v[214:217], v[226:229], v[42:45]
	v_mfma_f32_16x16x32_bf16 v[34:37], v[206:209], v[234:237], v[34:37]
	v_mfma_f32_16x16x32_bf16 v[26:29], v[214:217], v[234:237], v[26:29]
	v_mfma_f32_16x16x32_bf16 v[18:21], v[206:209], v[242:245], v[18:21]
	ds_read_b128 v[134:137], v175 offset:1024
	v_mfma_f32_16x16x32_bf16 v[10:13], v[214:217], v[242:245], v[10:13]
	v_mfma_f32_16x16x32_bf16 v[6:9], v[206:209], v[250:253], v[6:9]
	v_mfma_f32_16x16x32_bf16 v[2:5], v[214:217], v[250:253], v[2:5]
	v_mfma_f32_16x16x32_bf16 v[50:53], v[210:213], v[230:233], v[50:53]
	ds_read_b128 v[138:141], v175 offset:2048
	v_mfma_f32_16x16x32_bf16 v[42:45], v[218:221], v[230:233], v[42:45]
	v_mfma_f32_16x16x32_bf16 v[34:37], v[210:213], v[238:241], v[34:37]
	v_mfma_f32_16x16x32_bf16 v[26:29], v[218:221], v[238:241], v[26:29]
	v_mfma_f32_16x16x32_bf16 v[18:21], v[210:213], v[246:249], v[18:21]
	ds_read_b128 v[142:145], v175 offset:3072
	v_mfma_f32_16x16x32_bf16 v[10:13], v[218:221], v[246:249], v[10:13]
	v_mfma_f32_16x16x32_bf16 v[6:9], v[210:213], v[222:225], v[6:9]
	v_mfma_f32_16x16x32_bf16 v[2:5], v[218:221], v[222:225], v[2:5]
	s_add_i32 s60, s60, 2
	s_add_u32 s28, s28, 0x100
	s_addc_u32 s29, s29, 0
	s_add_u32 s58, s58, 0x100
	s_addc_u32 s59, s59, 0
	s_cmpk_gt_u32 s60, 0x55
	s_barrier
	s_cbranch_scc0 .LBB0_1297
	s_branch .Lp10_loop_exit
